# attention loop issue trims: shuffle lane addresses in 4 ops instead of 17, one lgkmcnt wait per MFMA pair, hazard pad sized to what is still owed; on top of branch-free selects
# baseline (speedup 1.0000x reference)
; #define LAS __attribute__((address_space(3)))
; __device__ __forceinline__ unsigned pk2(float lo, float hi) { const f32x2 v = {lo, hi}; const bf16x2_t b = __builtin_convertvector(v, bf16x2_t); return __builtin_bit_cast(unsigned, b); }
; __device__ __forceinline__ void attn_unit(Frame& F, int b, int h, int qt, int kb_lo, int nkb, const bf16* QB, const bf16* KB, const bf16* VT, bf16* OUT, float bias2, f32x4* part, float* tpart) {
;     ...
;             const float Y3 = carry, Y2 = Y3 * GT[3], Y1 = Y2 * GT[2], Y0 = Y1 * GT[1];
;             carry = Y0 * GT[0];
;             const float f[4] = {Y0 * X[0], Y1 * X[1], Y2 * X[2], Y3 * X[3]};
;             bf16x8 pf[2];
; #pragma unroll
;             for (int ks = 0; ks < 2; ++ks) { u32x4 pw; pw.x = pk2(bt[2 * ks][0] * f[2 * ks], bt[2 * ks][1] * f[2 * ks]); pw.y = pk2(bt[2 * ks][2] * f[2 * ks], bt[2 * ks][3] * f[2 * ks]);
;                 pw.z = pk2(bt[2 * ks + 1][0] * f[2 * ks + 1], bt[2 * ks + 1][1] * f[2 * ks + 1]); pw.w = pk2(bt[2 * ks + 1][2] * f[2 * ks + 1], bt[2 * ks + 1][3] * f[2 * ks + 1]); pf[ks] = __builtin_bit_cast(bf16x8, pw); }
; #pragma unroll
;             for (int dt = 0; dt < 8; ++dt)
; #pragma unroll
;                 for (int ks = 0; ks < 2; ++ks) { const LAS bf16* vp = Vb + (16 * dt + li) * 72 + 32 * ks + 4 * g;
;                     const u32x2 a0 = *(const LAS u32x2*)vp, a1 = *(const LAS u32x2*)(vp + 16); const u32x4 av = (u32x4){a0.x, a0.y, a1.x, a1.y};
;                     oacc[dt] = __builtin_amdgcn_mfma_f32_16x16x32_bf16(__builtin_bit_cast(bf16x8, av), pf[ks], oacc[dt], 0, 0, 0); }
.LBB0_1058:
	s_or_b64 exec, exec, s[4:5]
	s_waitcnt lgkmcnt(5)
	v_mul_f32_e32 v137, v140, v141
	v_pk_mul_f32 v[140:141], v[104:105], v[100:101]
	s_waitcnt lgkmcnt(2)
	v_mul_f32_e32 v101, v102, v131
	s_waitcnt lgkmcnt(1)
	v_mul_f32_e32 v101, v101, v135
	v_mul_f32_e32 v137, v137, v142
	v_mul_f32_e32 v100, v133, v134
	s_waitcnt lgkmcnt(0)
	v_mul_f32_e32 v101, v101, v136
	v_mul_f32_e32 v137, v137, v143
	v_mul_f32_e32 v100, v100, v138
	v_mul_f32_e32 v101, v81, v101
	v_mul_f32_e32 v100, v100, v139
	v_mul_f32_e32 v102, v137, v101
	v_pk_mul_f32 v[92:93], v[108:109], v[92:93]
	v_mul_f32_e32 v109, v100, v102
	v_mul_f32_e32 v88, v127, v88
	v_pk_mul_f32 v[86:87], v[110:111], v[86:87]
	s_mul_i32 s4, s27, 0x4800
	v_mul_f32_e32 v100, v116, v109
	v_mul_f32_e32 v104, v117, v102
	v_mul_f32_e32 v108, v81, v103
	v_pk_mul_f32 v[86:87], v[86:87], v[100:101] op_sel_hi:[1,0]
	v_pk_mul_f32 v[88:89], v[88:89], v[100:101] op_sel_hi:[1,0]
	v_add3_u32 v81, v77, s4, v73
	v_add_u32_e32 v183, 0x8800, v81
	v_add_u32_e32 v164, 0x9000, v81
	v_add_u32_e32 v165, 0x9800, v81
	v_add_u32_e32 v166, 0xa000, v81
	v_add_u32_e32 v167, 0xa800, v81
	v_add_u32_e32 v168, 0xb000, v81
	v_add_u32_e32 v169, 0xb800, v81
	v_add_u32_e32 v182, 0xc000, v81
	ds_read2_b64 v[184:187], v183 offset1:4
	ds_read2_b64 v[188:191], v183 offset0:8 offset1:12
	ds_read2_b64 v[192:195], v164 offset0:32 offset1:36
	ds_read2_b64 v[196:199], v164 offset0:40 offset1:44
	ds_read2_b64 v[200:203], v165 offset0:64 offset1:68
	ds_read2_b64 v[204:207], v165 offset0:72 offset1:76
	v_cvt_pk_bf16_f32 v86, v86, v87
	v_cvt_pk_bf16_f32 v87, v88, v89
	v_pk_mul_f32 v[88:89], v[92:93], v[104:105] op_sel_hi:[1,0]
	v_pk_mul_f32 v[96:97], v[106:107], v[96:97]
	v_mul_f32_e32 v106, v132, v101
	v_mul_f32_e32 v90, v128, v90
	v_pk_mul_f32 v[90:91], v[90:91], v[104:105] op_sel_hi:[1,0]
	v_cvt_pk_bf16_f32 v88, v88, v89
	v_cvt_pk_bf16_f32 v89, v90, v91
	v_mul_f32_e32 v94, v129, v94
	v_pk_mul_f32 v[94:95], v[94:95], v[106:107] op_sel_hi:[1,0]
	s_nop 0
	s_waitcnt lgkmcnt(5)
	v_mfma_f32_16x16x32_bf16 v[30:33], v[184:187], v[86:89], v[30:33]
	ds_read2_b64 v[184:187], v166 offset0:96 offset1:100
	v_mul_f32_e32 v98, v130, v98
	v_cvt_pk_bf16_f32 v105, v94, v95
	v_pk_mul_f32 v[94:95], v[140:141], v[108:109] op_sel_hi:[1,0]
	v_pk_mul_f32 v[96:97], v[96:97], v[106:107] op_sel_hi:[1,0]
	v_cvt_pk_bf16_f32 v106, v94, v95
	v_pk_mul_f32 v[94:95], v[98:99], v[108:109] op_sel_hi:[1,0]
	v_cvt_pk_bf16_f32 v104, v96, v97
	v_cvt_pk_bf16_f32 v107, v94, v95
	s_nop 1
	s_waitcnt lgkmcnt(5)
	v_mfma_f32_16x16x32_bf16 v[30:33], v[188:191], v[104:107], v[30:33]
	ds_read2_b64 v[188:191], v166 offset0:104 offset1:108
	s_waitcnt lgkmcnt(4)
	v_mfma_f32_16x16x32_bf16 v[26:29], v[192:195], v[86:89], v[26:29]
	ds_read2_b64 v[192:195], v167 offset0:128 offset1:132
	v_mfma_f32_16x16x32_bf16 v[26:29], v[196:199], v[104:107], v[26:29]
	ds_read2_b64 v[196:199], v167 offset0:136 offset1:140
	s_waitcnt lgkmcnt(4)
	v_mfma_f32_16x16x32_bf16 v[22:25], v[200:203], v[86:89], v[22:25]
	ds_read2_b64 v[200:203], v168 offset0:160 offset1:164
	v_mfma_f32_16x16x32_bf16 v[22:25], v[204:207], v[104:107], v[22:25]
	ds_read2_b64 v[204:207], v168 offset0:168 offset1:172
	s_waitcnt lgkmcnt(4)
	v_mfma_f32_16x16x32_bf16 v[18:21], v[184:187], v[86:89], v[18:21]
	ds_read2_b64 v[184:187], v169 offset0:192 offset1:196
	v_mfma_f32_16x16x32_bf16 v[18:21], v[188:191], v[104:107], v[18:21]
	ds_read2_b64 v[188:191], v169 offset0:200 offset1:204
	s_waitcnt lgkmcnt(4)
	v_mfma_f32_16x16x32_bf16 v[14:17], v[192:195], v[86:89], v[14:17]
	ds_read2_b64 v[192:195], v182 offset0:224 offset1:228
	v_mfma_f32_16x16x32_bf16 v[14:17], v[196:199], v[104:107], v[14:17]
	ds_read2_b64 v[196:199], v182 offset0:232 offset1:236
	s_waitcnt lgkmcnt(4)
	v_mfma_f32_16x16x32_bf16 v[10:13], v[200:203], v[86:89], v[10:13]
	v_mfma_f32_16x16x32_bf16 v[10:13], v[204:207], v[104:107], v[10:13]
	s_waitcnt lgkmcnt(2)
	v_mfma_f32_16x16x32_bf16 v[6:9], v[184:187], v[86:89], v[6:9]
	v_mfma_f32_16x16x32_bf16 v[6:9], v[188:191], v[104:107], v[6:9]
	v_mul_f32_e32 v81, v112, v113
	v_mul_f32_e32 v81, v81, v114
	s_waitcnt lgkmcnt(1)
	v_mfma_f32_16x16x32_bf16 v[2:5], v[192:195], v[86:89], v[2:5]
	v_mul_f32_e32 v81, v81, v115
	v_mul_f32_e32 v81, v81, v109
	s_waitcnt lgkmcnt(0)
	v_mfma_f32_16x16x32_bf16 v[2:5], v[196:199], v[104:107], v[2:5]

; #define LAS __attribute__((address_space(3)))
; __device__ __forceinline__ float ex2(float x) { return __builtin_amdgcn_exp2f(x); }
; __device__ __forceinline__ float rcpf_(float x) { return __builtin_amdgcn_rcpf(x); }
; __device__ __forceinline__ void attn_unit(Frame& F, int b, int h, int qt, int kb_lo, int nkb, const bf16* QB, const bf16* KB, const bf16* VT, bf16* OUT, float bias2, f32x4* part, float* tpart) {
;     ...
;     for (int it = 0; it < nkb; ++it) {
;         const int kb = kb_lo + nkb - 1 - it, buf = it & 1; const bool more = (it + 1 < nkb);
;         if (more) { const int k2 = kb - 1;
;             lk[0] = *(const u32x4*)(kg + (size_t)(k2 * 64 + kr0) * BW); lk[1] = *(const u32x4*)(kg + (size_t)(k2 * 64 + kr0 + 32) * BW);
;             lv[0] = *(const u32x4*)(vg + (size_t)vr0 * SEQ + k2 * 64); lv[1] = *(const u32x4*)(vg + (size_t)(vr0 + 64) * SEQ + k2 * 64); }
;         if (kb * 64 < q0 + 15) {
;             const LAS bf16* Kb = Ks + buf * (64 * 136); const LAS bf16* Vb = Vs + buf * (128 * 72);
;             f32x4 s[4];
; #pragma unroll
;             for (int st = 0; st < 4; ++st) { s[st] = (f32x4){bias2, bias2, bias2, bias2};
; #pragma unroll
;                 for (int ks = 0; ks < 4; ++ks) { const bf16x8 af = *(const LAS bf16x8*)(Kb + (16 * st + li) * 136 + 32 * ks + 8 * g); s[st] = __builtin_amdgcn_mfma_f32_16x16x32_bf16(af, qf[ks], s[st], 0, 0, 0); } }
;             float om[4][4], bt[4][4], lt[4], X[4], GT[4];
;             if (kb * 64 + 63 >= q0) {
;                 const int kbase = kb * 64 + 4 * g;
; #pragma unroll
;                 for (int st = 0; st < 4; ++st)
; #pragma unroll
;                     for (int r = 0; r < 4; ++r) { const float e = ex2(s[st][r]); float o = rcpf_(1.0f + e), bb = e * o;
;                         if (kbase + 16 * st + r >= qpos) { o = 1.f; bb = 0.f; }
;                         om[st][r] = o; bt[st][r] = bb; }
.LBB0_1060:
	v_add_u32_e32 v58, s26, v119
	s_add_i32 s2, s26, 0xffffff81
	v_add_u32_e32 v56, 0xffffff81, v58
	v_add_u32_e32 v58, 0xffffffa1, v58
	v_ashrrev_i32_e32 v57, 31, v56
	v_ashrrev_i32_e32 v59, 31, v58
	s_ashr_i32 s3, s2, 31
	v_lshlrev_b64 v[56:57], 10, v[56:57]
	v_lshlrev_b64 v[58:59], 10, v[58:59]
	s_lshl_b64 s[2:3], s[2:3], 1
	v_lshl_add_u64 v[56:57], v[78:79], 0, v[56:57]
	v_lshl_add_u64 v[60:61], v[78:79], 0, v[58:59]
	v_lshl_add_u64 v[64:65], v[82:83], 0, s[2:3]
	v_lshl_add_u64 v[68:69], v[84:85], 0, s[2:3]
	global_load_dwordx4 v[56:59], v[56:57], off
	s_nop 0
	global_load_dwordx4 v[60:63], v[60:61], off
	s_nop 0
	global_load_dwordx4 v[64:67], v[64:65], off
	s_nop 0
	global_load_dwordx4 v[68:71], v[68:69], off
	s_sub_i32 s2, s26, 63
	s_and_b32 s27, s24, 1
	v_cmp_lt_i32_e64 s[4:5], s2, v124
	s_and_saveexec_b64 s[2:3], s[4:5]
	s_cbranch_execz .LBB0_1059
	s_mul_i32 s4, s27, 0x4400
	v_add3_u32 v106, v120, s4, v121
	ds_read_b128 v[184:187], v106
	ds_read_b128 v[188:191], v106 offset:64
	ds_read_b128 v[192:195], v106 offset:128
	ds_read_b128 v[196:199], v106 offset:192
	ds_read_b128 v[200:203], v106 offset:4352
	ds_read_b128 v[204:207], v106 offset:4416
	v_cmp_ge_i32_e64 s[4:5], s26, v118
	s_waitcnt vmcnt(4) lgkmcnt(4)
	v_mfma_f32_16x16x32_bf16 v[86:89], v[184:187], v[48:51], v[52:55]
	ds_read_b128 v[184:187], v106 offset:4480
	v_mfma_f32_16x16x32_bf16 v[86:89], v[188:191], v[44:47], v[86:89]
	ds_read_b128 v[188:191], v106 offset:4544
	s_waitcnt lgkmcnt(4)
	v_mfma_f32_16x16x32_bf16 v[86:89], v[192:195], v[40:43], v[86:89]
	ds_read_b128 v[192:195], v106 offset:8704
	v_mfma_f32_16x16x32_bf16 v[86:89], v[196:199], v[36:39], v[86:89]
	ds_read_b128 v[196:199], v106 offset:8768
	s_waitcnt lgkmcnt(4)
	v_mfma_f32_16x16x32_bf16 v[90:93], v[200:203], v[48:51], v[52:55]
	ds_read_b128 v[200:203], v106 offset:8832
	v_mfma_f32_16x16x32_bf16 v[90:93], v[204:207], v[44:47], v[90:93]
	ds_read_b128 v[204:207], v106 offset:8896
	s_waitcnt lgkmcnt(4)
	v_mfma_f32_16x16x32_bf16 v[90:93], v[184:187], v[40:43], v[90:93]
	ds_read_b128 v[184:187], v106 offset:13056
	v_exp_f32_e32 v116, v86
	v_exp_f32_e32 v117, v87
	v_exp_f32_e32 v150, v88
	v_mfma_f32_16x16x32_bf16 v[90:93], v[188:191], v[36:39], v[90:93]
	ds_read_b128 v[188:191], v106 offset:13120
	v_exp_f32_e32 v149, v89
	v_add_f32_e32 v157, 1.0, v116
	v_add_f32_e32 v158, 1.0, v117
	s_waitcnt lgkmcnt(4)
	v_mfma_f32_16x16x32_bf16 v[94:97], v[192:195], v[48:51], v[52:55]
	ds_read_b128 v[192:195], v106 offset:13184
	v_add_f32_e32 v156, 1.0, v150
	v_add_f32_e32 v155, 1.0, v149
	v_mfma_f32_16x16x32_bf16 v[94:97], v[196:199], v[44:47], v[94:97]
	ds_read_b128 v[196:199], v106 offset:13248
	s_waitcnt lgkmcnt(4)
	v_mfma_f32_16x16x32_bf16 v[94:97], v[200:203], v[40:43], v[94:97]
	v_exp_f32_e32 v114, v90
	v_exp_f32_e32 v115, v91
	v_exp_f32_e32 v144, v92
	v_mfma_f32_16x16x32_bf16 v[94:97], v[204:207], v[36:39], v[94:97]
	v_exp_f32_e32 v141, v93
	v_add_f32_e32 v153, 1.0, v114
	v_add_f32_e32 v154, 1.0, v115
	s_waitcnt lgkmcnt(2)
	v_mfma_f32_16x16x32_bf16 v[98:101], v[184:187], v[48:51], v[52:55]
	v_add_f32_e32 v152, 1.0, v144
	v_add_f32_e32 v151, 1.0, v141
	v_mfma_f32_16x16x32_bf16 v[98:101], v[188:191], v[44:47], v[98:101]
	s_waitcnt lgkmcnt(0)
	v_mfma_f32_16x16x32_bf16 v[98:101], v[192:195], v[40:43], v[98:101]
	v_exp_f32_e32 v112, v94
	v_exp_f32_e32 v113, v95
	v_exp_f32_e32 v140, v96
	v_mfma_f32_16x16x32_bf16 v[98:101], v[196:199], v[36:39], v[98:101]
	v_exp_f32_e32 v137, v97
	v_add_f32_e32 v147, 1.0, v112
	v_add_f32_e32 v148, 1.0, v113
	v_add_f32_e32 v146, 1.0, v140
	v_add_f32_e32 v145, 1.0, v137
	s_nop 2
	v_exp_f32_e32 v110, v98
	v_exp_f32_e32 v111, v99
	v_exp_f32_e32 v136, v100
	v_exp_f32_e32 v135, v101
	v_add_f32_e32 v142, 1.0, v110
	v_add_f32_e32 v143, 1.0, v111
	v_add_f32_e32 v139, 1.0, v136
	v_add_f32_e32 v138, 1.0, v135
	s_and_saveexec_b64 s[6:7], s[4:5]
	s_xor_b64 s[16:17], exec, s[6:7]
	s_cbranch_execz .LBB0_1063
; __device__ __forceinline__ float ex2(float x) { return __builtin_amdgcn_exp2f(x); }
; __device__ __forceinline__ float rcpf_(float x) { return __builtin_amdgcn_rcpf(x); }
; __device__ __forceinline__ void attn_unit(Frame& F, int b, int h, int qt, int kb_lo, int nkb, const bf16* QB, const bf16* KB, const bf16* VT, bf16* OUT, float bias2, f32x4* part, float* tpart) {
;     ...
;             if (kb * 64 + 63 >= q0) {
;                 const int kbase = kb * 64 + 4 * g;
; #pragma unroll
;                 for (int st = 0; st < 4; ++st)
; #pragma unroll
;                     for (int r = 0; r < 4; ++r) { const float e = ex2(s[st][r]); float o = rcpf_(1.0f + e), bb = e * o;
;                         if (kbase + 16 * st + r >= qpos) { o = 1.f; bb = 0.f; }
;                         om[st][r] = o; bt[st][r] = bb; }
	v_rcp_f32_e32 v88, v157
	v_rcp_f32_e32 v89, v158
	v_add_u32_e32 v130, s26, v72
	v_subrev_u32_e32 v91, 62, v130
	v_cmp_lt_i32_e64 s[4:5], v91, v1
	v_rcp_f32_e32 v91, v156
	v_rcp_f32_e32 v92, v155
	v_subrev_u32_e32 v90, 63, v130
	v_pk_mul_f32 v[86:87], v[116:117], v[88:89]
	v_cndmask_b32_e64 v109, 1.0, v89, s[4:5]
	v_subrev_u32_e32 v89, 61, v130
	v_cndmask_b32_e64 v87, 0, v87, s[4:5]
	v_cmp_lt_i32_e64 s[6:7], v90, v76
	v_cmp_lt_i32_e64 s[4:5], v89, v76
	v_subrev_u32_e32 v93, 60, v130
	v_cndmask_b32_e64 v108, 1.0, v88, s[6:7]
	v_mul_f32_e32 v88, v150, v91
	v_cndmask_b32_e64 v134, 1.0, v91, s[4:5]
	v_rcp_f32_e32 v90, v153
	v_rcp_f32_e32 v91, v154
	v_cndmask_b32_e64 v88, 0, v88, s[4:5]
	v_mul_f32_e32 v89, v149, v92
	v_cmp_lt_i32_e64 s[4:5], v93, v76
	v_subrev_u32_e32 v94, 46, v130
	v_rcp_f32_e32 v96, v151
	v_cndmask_b32_e64 v89, 0, v89, s[4:5]
	v_cndmask_b32_e64 v127, 1.0, v92, s[4:5]
	v_cmp_lt_i32_e64 s[4:5], v94, v1
	v_rcp_f32_e32 v94, v152
	v_pk_mul_f32 v[92:93], v[114:115], v[90:91]
	v_subrev_u32_e32 v95, 47, v130
	v_cndmask_b32_e64 v107, 1.0, v91, s[4:5]
	v_subrev_u32_e32 v91, 45, v130
	v_cndmask_b32_e64 v86, 0, v86, s[6:7]
	v_cndmask_b32_e64 v93, 0, v93, s[4:5]
	v_cmp_lt_i32_e64 s[6:7], v95, v76
	v_cmp_lt_i32_e64 s[4:5], v91, v76
	v_subrev_u32_e32 v97, 44, v130
	v_cndmask_b32_e64 v106, 1.0, v90, s[6:7]
	v_mul_f32_e32 v90, v144, v94
	v_cndmask_b32_e64 v133, 1.0, v94, s[4:5]
	v_rcp_f32_e32 v94, v147
	v_rcp_f32_e32 v95, v148
	v_cndmask_b32_e64 v90, 0, v90, s[4:5]
	v_mul_f32_e32 v91, v141, v96
	v_cmp_lt_i32_e64 s[4:5], v97, v76
	v_subrev_u32_e32 v98, 30, v130
	v_subrev_u32_e32 v99, 31, v130
	v_cndmask_b32_e64 v91, 0, v91, s[4:5]
	v_cndmask_b32_e64 v128, 1.0, v96, s[4:5]
	v_cmp_lt_i32_e64 s[4:5], v98, v1
	v_rcp_f32_e32 v98, v146
	v_pk_mul_f32 v[96:97], v[112:113], v[94:95]
	v_cndmask_b32_e64 v105, 1.0, v95, s[4:5]
	v_subrev_u32_e32 v95, 29, v130
	v_cndmask_b32_e64 v92, 0, v92, s[6:7]
	v_cndmask_b32_e64 v97, 0, v97, s[4:5]
	v_cmp_lt_i32_e64 s[6:7], v99, v76
	v_cmp_lt_i32_e64 s[4:5], v95, v76
	v_rcp_f32_e32 v100, v145
	v_cndmask_b32_e64 v104, 1.0, v94, s[6:7]
	v_mul_f32_e32 v94, v140, v98
	v_cndmask_b32_e64 v132, 1.0, v98, s[4:5]
	v_rcp_f32_e32 v98, v142
	v_rcp_f32_e32 v99, v143
	v_subrev_u32_e32 v101, 28, v130
	v_cndmask_b32_e64 v94, 0, v94, s[4:5]
	v_cmp_lt_i32_e64 s[4:5], v101, v76
	v_mul_f32_e32 v95, v137, v100
	v_add_u32_e32 v102, -14, v130
	v_cndmask_b32_e64 v129, 1.0, v100, s[4:5]
	v_pk_mul_f32 v[100:101], v[110:111], v[98:99]
	v_rcp_f32_e32 v110, v139
	v_cndmask_b32_e64 v95, 0, v95, s[4:5]
	v_add_u32_e32 v103, -15, v130
	v_cmp_lt_i32_e64 s[4:5], v102, v1
	v_rcp_f32_e32 v111, v138
	v_cndmask_b32_e64 v96, 0, v96, s[6:7]
	v_cmp_lt_i32_e64 s[6:7], v103, v76
	v_cndmask_b32_e64 v103, 1.0, v99, s[4:5]
	v_add_u32_e32 v99, -13, v130
	v_cndmask_b32_e64 v101, 0, v101, s[4:5]
	v_cmp_lt_i32_e64 s[4:5], v99, v76
	v_cndmask_b32_e64 v102, 1.0, v98, s[6:7]
	v_mul_f32_e32 v98, v136, v110
	v_cndmask_b32_e64 v131, 1.0, v110, s[4:5]
	v_add_u32_e32 v110, -12, v130
	v_cndmask_b32_e64 v98, 0, v98, s[4:5]
	v_mul_f32_e32 v99, v135, v111
	v_cmp_lt_i32_e64 s[4:5], v110, v76
	v_cndmask_b32_e64 v100, 0, v100, s[6:7]
	s_nop 0
	v_cndmask_b32_e64 v99, 0, v99, s[4:5]
	v_cndmask_b32_e64 v130, 1.0, v111, s[4:5]

; __device__ __forceinline__ void attn_unit(Frame& F, int b, int h, int qt, int kb_lo, int nkb, const bf16* QB, const bf16* KB, const bf16* VT, bf16* OUT, float bias2, f32x4* part, float* tpart) {
;     ...
;                 const float xa = __shfl_xor(lt[st], 16), xb = __shfl_xor(lt[st], 32), xc = __shfl_xor(lt[st], 48);
;                 X[st] = (g == 0) ? xa * xb * xc : (g == 1) ? xb * xc : (g == 2) ? xa : 1.f;
;                 GT[st] = lt[st] * xa * xb * xc;
.LBB0_1065:
	s_or_b64 exec, exec, s[4:5]
	v_lshlrev_b32_e32 v110, 2, v218
	v_xor_b32_e32 v135, 64, v110
	v_xor_b32_e32 v136, 0x80, v110
	v_xor_b32_e32 v137, 0xc0, v110
	v_mul_f32_e32 v111, v127, v134
	v_mul_f32_e32 v110, v111, v109
	v_mul_f32_e32 v112, v110, v108
	ds_bpermute_b32 v113, v135, v112
	ds_bpermute_b32 v114, v136, v112
	ds_bpermute_b32 v115, v137, v112
	s_orn2_b64 s[6:7], vcc, s[0:1]
	s_nand_b64 s[16:17], s[0:1], s[38:39]
	s_waitcnt lgkmcnt(0)
	v_mul_f32_e32 v108, v114, v115
	v_cndmask_b32_e64 v116, 1.0, v113, s[6:7]
	v_cndmask_b32_e64 v108, 1.0, v108, s[16:17]
	v_mul_f32_e32 v116, v116, v108
	v_mul_f32_e32 v109, v128, v133
	v_mul_f32_e32 v108, v109, v107
	v_mul_f32_e32 v133, v108, v106
	ds_bpermute_b32 v134, v135, v133
	ds_bpermute_b32 v138, v136, v133
	ds_bpermute_b32 v139, v137, v133
	s_waitcnt lgkmcnt(0)
	v_mul_f32_e32 v106, v138, v139
	v_cndmask_b32_e64 v117, 1.0, v134, s[6:7]
	v_cndmask_b32_e64 v106, 1.0, v106, s[16:17]
	v_mul_f32_e32 v117, v117, v106
	v_mul_f32_e32 v107, v129, v132
	v_mul_f32_e32 v106, v107, v105
	v_mul_f32_e32 v140, v106, v104
	ds_bpermute_b32 v141, v135, v140
	ds_bpermute_b32 v142, v136, v140
	ds_bpermute_b32 v143, v137, v140
	s_waitcnt lgkmcnt(0)
	v_mul_f32_e32 v104, v142, v143
	v_cndmask_b32_e64 v132, 1.0, v141, s[6:7]
	v_cndmask_b32_e64 v104, 1.0, v104, s[16:17]
	v_mul_f32_e32 v132, v132, v104
	v_mul_f32_e32 v105, v130, v131
	v_mul_f32_e32 v104, v105, v103
	v_mul_f32_e32 v102, v104, v102
	ds_bpermute_b32 v131, v135, v102
	ds_bpermute_b32 v135, v136, v102
	ds_bpermute_b32 v136, v137, v102
	s_waitcnt lgkmcnt(0)
	v_mul_f32_e32 v104, v135, v136
	v_cndmask_b32_e64 v103, 1.0, v131, s[6:7]
	v_cndmask_b32_e64 v104, 1.0, v104, s[16:17]
	v_mul_f32_e32 v103, v103, v104
	s_mov_b64 s[4:5], exec
	s_branch .LBB0_1058
